# prologue x->bf16 loop: compiler's full vmcnt drain right after the row-ahead loads replaced by counted waits per row buffer (15..12 / 16 / 16 / 12)
# speedup vs baseline: 1.0036x; 1.0015x over previous
.LBB0_136:
	s_or_b64 exec, exec, s[10:11]
	s_waitcnt vmcnt(15)
	v_mul_f32_e32 v67, v7, v7
	v_mul_f32_e32 v71, v9, v9
	v_fmac_f32_e32 v67, v6, v6
	v_fmac_f32_e32 v71, v8, v8
	v_add_f32_e32 v67, v67, v71
	s_waitcnt vmcnt(14)
	v_mul_f32_e32 v71, v11, v11
	v_mul_f32_e32 v80, v13, v13
	v_fmac_f32_e32 v71, v10, v10
	v_fmac_f32_e32 v80, v12, v12
	v_add_f32_e32 v71, v71, v80
	v_add_f32_e32 v67, v67, v71
	s_waitcnt vmcnt(13)
	v_mul_f32_e32 v71, v15, v15
	v_mul_f32_e32 v80, v17, v17
	v_fmac_f32_e32 v71, v14, v14
	v_fmac_f32_e32 v80, v16, v16
	v_add_f32_e32 v71, v71, v80
	v_add_f32_e32 v67, v71, v67
	s_waitcnt vmcnt(12)
	v_mul_f32_e32 v71, v19, v19
	v_mul_f32_e32 v80, v21, v21
	v_fmac_f32_e32 v71, v18, v18
	v_fmac_f32_e32 v80, v20, v20
	v_add_f32_e32 v71, v71, v80
	v_add_f32_e32 v67, v71, v67
	s_nop 1
	v_add_f32_dpp v67, v67, v67 quad_perm:[1,0,3,2] row_mask:0xf bank_mask:0xf bound_ctrl:1
	s_nop 1
	v_add_f32_dpp v67, v67, v67 quad_perm:[2,3,0,1] row_mask:0xf bank_mask:0xf bound_ctrl:1
	s_nop 1
	v_add_f32_dpp v67, v67, v67 row_half_mirror row_mask:0xf bank_mask:0xf bound_ctrl:1
	s_nop 1
	v_add_f32_dpp v67, v67, v67 row_mirror row_mask:0xf bank_mask:0xf bound_ctrl:1
	v_mov_b32_e32 v71, v67
	s_nop 1
	v_permlane16_swap_b32_e32 v67, v71
	v_add_f32_e32 v67, v67, v71
	v_mov_b32_e32 v71, v67
	s_nop 1
	v_permlane32_swap_b32_e32 v67, v71
	v_add_f32_e32 v67, v67, v71
	v_fmamk_f32 v67, v67, 0x3a800000, v1
	v_rsq_f32_e32 v71, v67
	s_and_saveexec_b64 s[10:11], s[4:5]
	s_cbranch_execz .LBB0_138
	v_lshl_add_u64 v[80:81], s[8:9], 0, v[74:75]
	global_store_dword v[80:81], v71, off

; __device__ __forceinline__ void prologue_phase(const Params& P, LAS unsigned char* lds, int G) {
;     ...
;         if (r1 < MTOT) XPROC(vb, r1);
.LBB0_140:
	s_or_b64 exec, exec, s[30:31]
	v_add_u32_e32 v80, s3, v70
	v_cmp_gt_i32_e64 s[10:11], s35, v80
	s_and_saveexec_b64 s[30:31], s[10:11]
	s_cbranch_execz .LBB0_144
	s_waitcnt vmcnt(16)
	v_mul_f32_e32 v71, v3, v3
	v_mul_f32_e32 v81, v5, v5
	v_fmac_f32_e32 v71, v2, v2
	v_fmac_f32_e32 v81, v4, v4
	v_add_f32_e32 v71, v71, v81
	v_mul_f32_e32 v81, v23, v23
	v_mul_f32_e32 v82, v25, v25
	v_fmac_f32_e32 v81, v22, v22
	v_fmac_f32_e32 v82, v24, v24
	v_add_f32_e32 v81, v81, v82
	v_add_f32_e32 v71, v71, v81
	v_mul_f32_e32 v81, v27, v27
	v_mul_f32_e32 v82, v29, v29
	v_fmac_f32_e32 v81, v26, v26
	v_fmac_f32_e32 v82, v28, v28
	v_add_f32_e32 v81, v81, v82
	v_add_f32_e32 v71, v81, v71
	v_mul_f32_e32 v81, v31, v31
	v_mul_f32_e32 v82, v33, v33
	v_fmac_f32_e32 v81, v30, v30
	v_fmac_f32_e32 v82, v32, v32
	v_add_f32_e32 v81, v81, v82
	v_add_f32_e32 v71, v81, v71
	s_nop 1
	v_add_f32_dpp v71, v71, v71 quad_perm:[1,0,3,2] row_mask:0xf bank_mask:0xf bound_ctrl:1
	s_nop 1
	v_add_f32_dpp v71, v71, v71 quad_perm:[2,3,0,1] row_mask:0xf bank_mask:0xf bound_ctrl:1
	s_nop 1
	v_add_f32_dpp v71, v71, v71 row_half_mirror row_mask:0xf bank_mask:0xf bound_ctrl:1
	s_nop 1
	v_add_f32_dpp v71, v71, v71 row_mirror row_mask:0xf bank_mask:0xf bound_ctrl:1
	v_mov_b32_e32 v81, v71
	s_nop 1
	v_permlane16_swap_b32_e32 v71, v81
	v_add_f32_e32 v71, v71, v81
	v_mov_b32_e32 v81, v71
	s_nop 1
	v_permlane32_swap_b32_e32 v71, v81
	v_add_f32_e32 v71, v71, v81
	v_fmamk_f32 v71, v71, 0x3a800000, v1
	v_rsq_f32_e32 v71, v71
	v_ashrrev_i32_e32 v81, 31, v80
	s_and_saveexec_b64 s[10:11], s[4:5]
	s_cbranch_execz .LBB0_143
	v_lshl_add_u64 v[82:83], v[80:81], 2, s[20:21]
	global_store_dword v[82:83], v71, off

; __device__ __forceinline__ void prologue_phase(const Params& P, LAS unsigned char* lds, int G) {
;     ...
;         if (r2 < MTOT) XPROC(vc, r2);
.LBB0_146:
	s_or_b64 exec, exec, s[10:11]
	v_add_u32_e32 v80, s19, v70
	v_cmp_gt_i32_e32 vcc, s35, v80
	s_and_saveexec_b64 s[10:11], vcc
	s_cbranch_execz .LBB0_150
	s_waitcnt vmcnt(16)
	v_mul_f32_e32 v71, v35, v35
	v_mul_f32_e32 v81, v37, v37
	v_fmac_f32_e32 v71, v34, v34
	v_fmac_f32_e32 v81, v36, v36
	v_add_f32_e32 v71, v71, v81
	v_mul_f32_e32 v81, v39, v39
	v_mul_f32_e32 v82, v41, v41
	v_fmac_f32_e32 v81, v38, v38
	v_fmac_f32_e32 v82, v40, v40
	v_add_f32_e32 v81, v81, v82
	v_add_f32_e32 v71, v81, v71
	v_mul_f32_e32 v81, v43, v43
	v_mul_f32_e32 v82, v45, v45
	v_fmac_f32_e32 v81, v42, v42
	v_fmac_f32_e32 v82, v44, v44
	v_add_f32_e32 v81, v81, v82
	v_add_f32_e32 v71, v81, v71
	v_mul_f32_e32 v81, v47, v47
	v_mul_f32_e32 v82, v49, v49
	v_fmac_f32_e32 v81, v46, v46
	v_fmac_f32_e32 v82, v48, v48
	v_add_f32_e32 v81, v81, v82
	v_add_f32_e32 v71, v81, v71
	s_nop 1
	v_add_f32_dpp v71, v71, v71 quad_perm:[1,0,3,2] row_mask:0xf bank_mask:0xf bound_ctrl:1
	s_nop 1
	v_add_f32_dpp v71, v71, v71 quad_perm:[2,3,0,1] row_mask:0xf bank_mask:0xf bound_ctrl:1
	s_nop 1
	v_add_f32_dpp v71, v71, v71 row_half_mirror row_mask:0xf bank_mask:0xf bound_ctrl:1
	s_nop 1
	v_add_f32_dpp v71, v71, v71 row_mirror row_mask:0xf bank_mask:0xf bound_ctrl:1
	v_mov_b32_e32 v81, v71
	s_nop 1
	v_permlane16_swap_b32_e32 v71, v81
	v_add_f32_e32 v71, v71, v81
	v_mov_b32_e32 v81, v71
	s_nop 1
	v_permlane32_swap_b32_e32 v71, v81
	v_add_f32_e32 v71, v71, v81
	v_fmamk_f32 v71, v71, 0x3a800000, v1
	v_rsq_f32_e32 v71, v71
	v_ashrrev_i32_e32 v81, 31, v80
	s_and_saveexec_b64 s[30:31], s[4:5]
	s_cbranch_execz .LBB0_149
	v_lshl_add_u64 v[82:83], v[80:81], 2, s[20:21]
	global_store_dword v[82:83], v71, off

; __device__ __forceinline__ void prologue_phase(const Params& P, LAS unsigned char* lds, int G) {
;     ...
;         if (r3 < MTOT) XPROC(vd, r3);
.LBB0_152:
	s_or_b64 exec, exec, s[10:11]
	s_and_saveexec_b64 s[10:11], s[6:7]
	s_cbranch_execz .LBB0_133
	s_waitcnt vmcnt(12)
	v_mul_f32_e32 v68, v63, v63
	v_mul_f32_e32 v70, v65, v65
	v_fmac_f32_e32 v68, v62, v62
	v_fmac_f32_e32 v70, v64, v64
	v_add_f32_e32 v68, v68, v70
	v_mul_f32_e32 v70, v59, v59
	v_mul_f32_e32 v71, v61, v61
	v_fmac_f32_e32 v70, v58, v58
	v_fmac_f32_e32 v71, v60, v60
	v_add_f32_e32 v70, v70, v71
	v_add_f32_e32 v68, v70, v68
	v_mul_f32_e32 v70, v55, v55
	v_mul_f32_e32 v71, v57, v57
	v_fmac_f32_e32 v70, v54, v54
	v_fmac_f32_e32 v71, v56, v56
	v_add_f32_e32 v70, v70, v71
	v_add_f32_e32 v68, v70, v68
	v_mul_f32_e32 v70, v51, v51
	v_mul_f32_e32 v71, v53, v53
	v_fmac_f32_e32 v70, v50, v50
	v_fmac_f32_e32 v71, v52, v52
	v_add_f32_e32 v70, v70, v71
	v_add_f32_e32 v68, v70, v68
	s_nop 1
	v_add_f32_dpp v68, v68, v68 quad_perm:[1,0,3,2] row_mask:0xf bank_mask:0xf bound_ctrl:1
	s_nop 1
	v_add_f32_dpp v68, v68, v68 quad_perm:[2,3,0,1] row_mask:0xf bank_mask:0xf bound_ctrl:1
	s_nop 1
	v_add_f32_dpp v68, v68, v68 row_half_mirror row_mask:0xf bank_mask:0xf bound_ctrl:1
	s_nop 1
	v_add_f32_dpp v68, v68, v68 row_mirror row_mask:0xf bank_mask:0xf bound_ctrl:1
	v_mov_b32_e32 v70, v68
	s_nop 1
	v_permlane16_swap_b32_e32 v68, v70
	v_add_f32_e32 v68, v68, v70
	v_mov_b32_e32 v70, v68
	s_nop 1
	v_permlane32_swap_b32_e32 v68, v70
	v_add_f32_e32 v68, v68, v70
	v_fmamk_f32 v68, v68, 0x3a800000, v1
	v_rsq_f32_e32 v68, v68
	s_and_saveexec_b64 s[6:7], s[4:5]
	s_cbranch_execz .LBB0_132
	v_lshl_add_u64 v[70:71], v[78:79], 2, s[20:21]
	global_store_dword v[70:71], v68, off
	s_branch .LBB0_132
